# GU2 epilogue: the eight rowss loads issued together at the top (one wait), same as W_in
# speedup vs baseline: 1.0097x; 1.0033x over previous
; __device__ __forceinline__ unsigned cvt_pk_bf16(float lo, float hi) { f32x2_t v = {lo, hi}; bf16x2_t b = __builtin_convertvector(v, bf16x2_t); return __builtin_bit_cast(unsigned, b); }
; __device__ __forceinline__ float silu_f(float g) { return g * __builtin_amdgcn_rcpf(1.0f + __builtin_amdgcn_exp2f(-1.44269504f * g)); }
;     __device__ __forceinline__ void operator()(const f32x4 (&acc)[2][2][4][2], const Unit& u, int wr, int wc, int fr, int fq) const {
;         const int row0 = u.pm * BM + wr * 64 + fr, col0 = u.pn * HALF + wc * 32 + 8 * fq;
; #pragma unroll
;         for (int ai = 0; ai < 2; ++ai)
; #pragma unroll
;             for (int m = 0; m < 4; ++m) {
;                 const int row = row0 + ai * HALF + m * 16;
;                 const float rs = rowss ? __builtin_amdgcn_rsqf(rowss[row] * (1.0f / 1024.0f) + 1e-6f) : 1.0f;
;                 bf16_t* rowp = O + (size_t)row * ldc + col0;
;                 const f32x4 g0 = acc[ai][0][m][0] * rs, g1 = acc[ai][0][m][1] * rs, u0 = acc[ai][1][m][0] * rs, u1 = acc[ai][1][m][1] * rs;
;                 u32x4 w;
;                 w.x = cvt_pk_bf16(silu_f(g0[0]) * u0[0], silu_f(g0[1]) * u0[1]); w.y = cvt_pk_bf16(silu_f(g0[2]) * u0[2], silu_f(g0[3]) * u0[3]);
;                 w.z = cvt_pk_bf16(silu_f(g1[0]) * u1[0], silu_f(g1[1]) * u1[1]); w.w = cvt_pk_bf16(silu_f(g1[2]) * u1[2], silu_f(g1[3]) * u1[3]);
;                 *(u32x4*)rowp = w;
.LBB0_1106:
	v_lshl_add_u32 v144, s20, 8, v152
	v_ashrrev_i32_e32 v145, 31, v144
	v_lshl_add_u64 v[150:151], v[144:145], 2, s[0:1]
	global_load_dword v145, v[150:151], off
	global_load_dword v230, v[150:151], off offset:64
	global_load_dword v231, v[150:151], off offset:128
	global_load_dword v232, v[150:151], off offset:192
	global_load_dword v233, v[150:151], off offset:512
	global_load_dword v234, v[150:151], off offset:576
	global_load_dword v235, v[150:151], off offset:640
	global_load_dword v236, v[150:151], off offset:704
	v_or_b32_e32 v162, 16, v144
	v_ashrrev_i32_e32 v163, 31, v162
	v_lshl_add_u64 v[166:167], v[162:163], 2, s[0:1]
	v_lshl_or_b32 v148, s48, 7, v154
	v_mov_b64_e32 v[146:147], s[6:7]
	v_ashrrev_i32_e32 v149, 31, v148
	v_mad_i64_i32 v[160:161], s[22:23], v144, s47, v[146:147]
	v_lshlrev_b64 v[148:149], 1, v[148:149]
	v_lshl_add_u64 v[160:161], v[160:161], 0, v[148:149]
	s_andn2_b64 vcc, exec, s[2:3]
	s_mov_b64 s[2:3], -1
	s_waitcnt vmcnt(0)
	v_fmamk_f32 v145, v145, 0x3a800000, v158
	v_rsq_f32_e32 v164, v145
	s_nop 0
	v_pk_mul_f32 v[126:127], v[126:127], v[164:165] op_sel_hi:[1,0]
	v_pk_mul_f32 v[124:125], v[124:125], v[164:165] op_sel_hi:[1,0]
	v_pk_mul_f32 v[122:123], v[122:123], v[164:165] op_sel_hi:[1,0]
	v_pk_mul_f32 v[120:121], v[120:121], v[164:165] op_sel_hi:[1,0]
	v_pk_mul_f32 v[118:119], v[118:119], v[164:165] op_sel_hi:[1,0]
	v_pk_mul_f32 v[116:117], v[116:117], v[164:165] op_sel_hi:[1,0]
	v_pk_mul_f32 v[114:115], v[114:115], v[164:165] op_sel_hi:[1,0]
	v_pk_mul_f32 v[112:113], v[112:113], v[164:165] op_sel_hi:[1,0]
	v_mul_f32_e32 v145, 0xbfb8aa3b, v124
	v_mul_f32_e32 v159, 0xbfb8aa3b, v125
	v_mul_f32_e32 v163, 0xbfb8aa3b, v126
	v_mul_f32_e32 v164, 0xbfb8aa3b, v127
	v_mul_f32_e32 v165, 0xbfb8aa3b, v120
	v_mul_f32_e32 v168, 0xbfb8aa3b, v121
	v_mul_f32_e32 v169, 0xbfb8aa3b, v122
	v_mul_f32_e32 v170, 0xbfb8aa3b, v123
	v_exp_f32_e32 v145, v145
	v_exp_f32_e32 v159, v159
	v_exp_f32_e32 v163, v163
	v_exp_f32_e32 v164, v164
	v_exp_f32_e32 v165, v165
	v_exp_f32_e32 v168, v168
	v_exp_f32_e32 v169, v169
	v_exp_f32_e32 v170, v170
	v_add_f32_e32 v145, 1.0, v145
	v_add_f32_e32 v159, 1.0, v159
	v_add_f32_e32 v163, 1.0, v163
	v_add_f32_e32 v171, 1.0, v164
	v_add_f32_e32 v172, 1.0, v165
	v_add_f32_e32 v173, 1.0, v168
	v_add_f32_e32 v174, 1.0, v169
	v_add_f32_e32 v175, 1.0, v170
	v_rcp_f32_e32 v164, v145
	v_rcp_f32_e32 v165, v159
	v_rcp_f32_e32 v168, v163
	v_rcp_f32_e32 v169, v171
	v_rcp_f32_e32 v170, v172
	v_rcp_f32_e32 v171, v173
	v_rcp_f32_e32 v172, v174
	v_rcp_f32_e32 v173, v175
	v_pk_mul_f32 v[124:125], v[124:125], v[164:165]
	v_pk_mul_f32 v[126:127], v[126:127], v[168:169]
	v_pk_mul_f32 v[120:121], v[120:121], v[170:171]
	v_pk_mul_f32 v[122:123], v[122:123], v[172:173]
	v_pk_mul_f32 v[116:117], v[116:117], v[124:125]
	v_pk_mul_f32 v[118:119], v[118:119], v[126:127]
	v_pk_mul_f32 v[120:121], v[112:113], v[120:121]
	v_pk_mul_f32 v[122:123], v[114:115], v[122:123]
	v_cvt_pk_bf16_f32 v112, v116, v117
	v_cvt_pk_bf16_f32 v113, v118, v119
	v_cvt_pk_bf16_f32 v114, v120, v121
	v_cvt_pk_bf16_f32 v115, v122, v123
	global_store_dwordx4 v[160:161], v[112:115], off
	s_nop 1
	s_nop 0
	v_or_b32_e32 v112, 32, v144
	v_mad_i64_i32 v[114:115], s[22:23], v162, s47, v[146:147]
	v_lshl_add_u64 v[114:115], v[114:115], 0, v[148:149]
	v_fmamk_f32 v113, v230, 0x3a800000, v158
	v_rsq_f32_e32 v116, v113
	v_ashrrev_i32_e32 v113, 31, v112
	v_lshl_add_u64 v[118:119], v[112:113], 2, s[0:1]
	v_pk_mul_f32 v[110:111], v[110:111], v[116:117] op_sel_hi:[1,0]
	v_pk_mul_f32 v[108:109], v[108:109], v[116:117] op_sel_hi:[1,0]
	v_pk_mul_f32 v[106:107], v[106:107], v[116:117] op_sel_hi:[1,0]
	v_pk_mul_f32 v[104:105], v[104:105], v[116:117] op_sel_hi:[1,0]
	v_pk_mul_f32 v[102:103], v[102:103], v[116:117] op_sel_hi:[1,0]
	v_pk_mul_f32 v[100:101], v[100:101], v[116:117] op_sel_hi:[1,0]
	v_pk_mul_f32 v[98:99], v[98:99], v[116:117] op_sel_hi:[1,0]
	v_pk_mul_f32 v[96:97], v[96:97], v[116:117] op_sel_hi:[1,0]
	v_mul_f32_e32 v113, 0xbfb8aa3b, v108
	v_mul_f32_e32 v116, 0xbfb8aa3b, v109
	v_mul_f32_e32 v117, 0xbfb8aa3b, v110
	v_mul_f32_e32 v120, 0xbfb8aa3b, v111
	v_mul_f32_e32 v121, 0xbfb8aa3b, v104
	v_mul_f32_e32 v122, 0xbfb8aa3b, v105
	v_mul_f32_e32 v123, 0xbfb8aa3b, v106
	v_mul_f32_e32 v124, 0xbfb8aa3b, v107
	v_exp_f32_e32 v113, v113
	v_exp_f32_e32 v116, v116
	v_exp_f32_e32 v117, v117
	v_exp_f32_e32 v120, v120
	v_exp_f32_e32 v121, v121
	v_exp_f32_e32 v122, v122
	v_exp_f32_e32 v123, v123
	v_exp_f32_e32 v124, v124
	v_add_f32_e32 v113, 1.0, v113
	v_add_f32_e32 v125, 1.0, v116
	v_add_f32_e32 v126, 1.0, v117
	v_add_f32_e32 v127, 1.0, v120
	v_add_f32_e32 v145, 1.0, v121
	v_add_f32_e32 v159, 1.0, v122
	v_add_f32_e32 v160, 1.0, v123
	v_add_f32_e32 v161, 1.0, v124
	v_rcp_f32_e32 v116, v113
	v_rcp_f32_e32 v117, v125
	v_rcp_f32_e32 v120, v126
	v_rcp_f32_e32 v121, v127
	v_rcp_f32_e32 v122, v145
	v_rcp_f32_e32 v123, v159
	v_rcp_f32_e32 v124, v160
	v_rcp_f32_e32 v125, v161
	v_pk_mul_f32 v[108:109], v[108:109], v[116:117]
	v_pk_mul_f32 v[110:111], v[110:111], v[120:121]
	v_pk_mul_f32 v[104:105], v[104:105], v[122:123]
	v_pk_mul_f32 v[106:107], v[106:107], v[124:125]
	v_pk_mul_f32 v[100:101], v[100:101], v[108:109]
	v_pk_mul_f32 v[102:103], v[102:103], v[110:111]
	v_pk_mul_f32 v[104:105], v[96:97], v[104:105]
	v_pk_mul_f32 v[106:107], v[98:99], v[106:107]
	v_cvt_pk_bf16_f32 v96, v100, v101
	v_cvt_pk_bf16_f32 v97, v102, v103
	v_cvt_pk_bf16_f32 v98, v104, v105
	v_cvt_pk_bf16_f32 v99, v106, v107
	global_store_dwordx4 v[114:115], v[96:99], off
	s_nop 1
	s_nop 0
	v_or_b32_e32 v96, 48, v144
	v_mad_i64_i32 v[98:99], s[22:23], v112, s47, v[146:147]
	v_lshl_add_u64 v[98:99], v[98:99], 0, v[148:149]
; __device__ __forceinline__ unsigned cvt_pk_bf16(float lo, float hi) { f32x2_t v = {lo, hi}; bf16x2_t b = __builtin_convertvector(v, bf16x2_t); return __builtin_bit_cast(unsigned, b); }
; __device__ __forceinline__ float silu_f(float g) { return g * __builtin_amdgcn_rcpf(1.0f + __builtin_amdgcn_exp2f(-1.44269504f * g)); }
;     __device__ __forceinline__ void operator()(const f32x4 (&acc)[2][2][4][2], const Unit& u, int wr, int wc, int fr, int fq) const {
;         const int row0 = u.pm * BM + wr * 64 + fr, col0 = u.pn * HALF + wc * 32 + 8 * fq;
; #pragma unroll
;         for (int ai = 0; ai < 2; ++ai)
; #pragma unroll
;             for (int m = 0; m < 4; ++m) {
;                 const int row = row0 + ai * HALF + m * 16;
;                 const float rs = rowss ? __builtin_amdgcn_rsqf(rowss[row] * (1.0f / 1024.0f) + 1e-6f) : 1.0f;
;                 bf16_t* rowp = O + (size_t)row * ldc + col0;
;                 const f32x4 g0 = acc[ai][0][m][0] * rs, g1 = acc[ai][0][m][1] * rs, u0 = acc[ai][1][m][0] * rs, u1 = acc[ai][1][m][1] * rs;
;                 u32x4 w;
;                 w.x = cvt_pk_bf16(silu_f(g0[0]) * u0[0], silu_f(g0[1]) * u0[1]); w.y = cvt_pk_bf16(silu_f(g0[2]) * u0[2], silu_f(g0[3]) * u0[3]);
;                 w.z = cvt_pk_bf16(silu_f(g1[0]) * u1[0], silu_f(g1[1]) * u1[1]); w.w = cvt_pk_bf16(silu_f(g1[2]) * u1[2], silu_f(g1[3]) * u1[3]);
;                 *(u32x4*)rowp = w;
	v_fmamk_f32 v97, v231, 0x3a800000, v158
	v_rsq_f32_e32 v100, v97
	v_ashrrev_i32_e32 v97, 31, v96
	v_lshl_add_u64 v[102:103], v[96:97], 2, s[0:1]
	v_pk_mul_f32 v[94:95], v[94:95], v[100:101] op_sel_hi:[1,0]
	v_pk_mul_f32 v[92:93], v[92:93], v[100:101] op_sel_hi:[1,0]
	v_pk_mul_f32 v[90:91], v[90:91], v[100:101] op_sel_hi:[1,0]
	v_pk_mul_f32 v[88:89], v[88:89], v[100:101] op_sel_hi:[1,0]
	v_pk_mul_f32 v[86:87], v[86:87], v[100:101] op_sel_hi:[1,0]
	v_pk_mul_f32 v[84:85], v[84:85], v[100:101] op_sel_hi:[1,0]
	v_pk_mul_f32 v[82:83], v[82:83], v[100:101] op_sel_hi:[1,0]
	v_pk_mul_f32 v[80:81], v[80:81], v[100:101] op_sel_hi:[1,0]
	v_mul_f32_e32 v97, 0xbfb8aa3b, v92
	v_mul_f32_e32 v100, 0xbfb8aa3b, v93
	v_mul_f32_e32 v101, 0xbfb8aa3b, v94
	v_mul_f32_e32 v104, 0xbfb8aa3b, v95
	v_mul_f32_e32 v105, 0xbfb8aa3b, v88
	v_mul_f32_e32 v106, 0xbfb8aa3b, v89
	v_mul_f32_e32 v107, 0xbfb8aa3b, v90
	v_mul_f32_e32 v108, 0xbfb8aa3b, v91
	v_exp_f32_e32 v97, v97
	v_exp_f32_e32 v100, v100
	v_exp_f32_e32 v101, v101
	v_exp_f32_e32 v104, v104
	v_exp_f32_e32 v105, v105
	v_exp_f32_e32 v106, v106
	v_exp_f32_e32 v107, v107
	v_exp_f32_e32 v108, v108
	v_add_f32_e32 v97, 1.0, v97
	v_add_f32_e32 v109, 1.0, v100
	v_add_f32_e32 v110, 1.0, v101
	v_add_f32_e32 v111, 1.0, v104
	v_add_f32_e32 v112, 1.0, v105
	v_add_f32_e32 v113, 1.0, v106
	v_add_f32_e32 v114, 1.0, v107
	v_add_f32_e32 v115, 1.0, v108
	v_rcp_f32_e32 v100, v97
	v_rcp_f32_e32 v101, v109
	v_rcp_f32_e32 v104, v110
	v_rcp_f32_e32 v105, v111
	v_rcp_f32_e32 v106, v112
	v_rcp_f32_e32 v107, v113
	v_rcp_f32_e32 v108, v114
	v_rcp_f32_e32 v109, v115
	v_pk_mul_f32 v[92:93], v[92:93], v[100:101]
	v_pk_mul_f32 v[94:95], v[94:95], v[104:105]
	v_pk_mul_f32 v[88:89], v[88:89], v[106:107]
	v_pk_mul_f32 v[90:91], v[90:91], v[108:109]
	v_pk_mul_f32 v[84:85], v[84:85], v[92:93]
	v_pk_mul_f32 v[86:87], v[86:87], v[94:95]
	v_pk_mul_f32 v[88:89], v[80:81], v[88:89]
	v_pk_mul_f32 v[90:91], v[82:83], v[90:91]
	v_cvt_pk_bf16_f32 v80, v84, v85
	v_cvt_pk_bf16_f32 v81, v86, v87
	v_cvt_pk_bf16_f32 v82, v88, v89
	v_cvt_pk_bf16_f32 v83, v90, v91
	global_store_dwordx4 v[98:99], v[80:83], off
	s_nop 1
	s_nop 0
	v_mad_i64_i32 v[82:83], s[22:23], v96, s47, v[146:147]
	v_lshl_add_u64 v[82:83], v[82:83], 0, v[148:149]
	v_fmamk_f32 v80, v232, 0x3a800000, v158
	v_rsq_f32_e32 v80, v80
	s_nop 0
	v_pk_mul_f32 v[78:79], v[78:79], v[80:81] op_sel_hi:[1,0]
	v_pk_mul_f32 v[76:77], v[76:77], v[80:81] op_sel_hi:[1,0]
	v_pk_mul_f32 v[74:75], v[74:75], v[80:81] op_sel_hi:[1,0]
	v_pk_mul_f32 v[72:73], v[72:73], v[80:81] op_sel_hi:[1,0]
	v_pk_mul_f32 v[70:71], v[70:71], v[80:81] op_sel_hi:[1,0]
	v_pk_mul_f32 v[68:69], v[68:69], v[80:81] op_sel_hi:[1,0]
	v_pk_mul_f32 v[66:67], v[66:67], v[80:81] op_sel_hi:[1,0]
	v_pk_mul_f32 v[64:65], v[64:65], v[80:81] op_sel_hi:[1,0]
	v_mul_f32_e32 v80, 0xbfb8aa3b, v76
	v_mul_f32_e32 v81, 0xbfb8aa3b, v77
	v_mul_f32_e32 v84, 0xbfb8aa3b, v78
	v_mul_f32_e32 v85, 0xbfb8aa3b, v79
	v_mul_f32_e32 v86, 0xbfb8aa3b, v72
	v_mul_f32_e32 v87, 0xbfb8aa3b, v73
	v_mul_f32_e32 v88, 0xbfb8aa3b, v74
	v_mul_f32_e32 v89, 0xbfb8aa3b, v75
	v_exp_f32_e32 v80, v80
	v_exp_f32_e32 v81, v81
	v_exp_f32_e32 v84, v84
	v_exp_f32_e32 v85, v85
	v_exp_f32_e32 v86, v86
	v_exp_f32_e32 v87, v87
	v_exp_f32_e32 v88, v88
	v_exp_f32_e32 v89, v89
	v_add_f32_e32 v80, 1.0, v80
	v_add_f32_e32 v81, 1.0, v81
	v_add_f32_e32 v84, 1.0, v84
	v_add_f32_e32 v85, 1.0, v85
	v_add_f32_e32 v86, 1.0, v86
	v_add_f32_e32 v87, 1.0, v87
	v_add_f32_e32 v88, 1.0, v88
	v_add_f32_e32 v89, 1.0, v89
	v_rcp_f32_e32 v80, v80
	v_rcp_f32_e32 v81, v81
	v_rcp_f32_e32 v84, v84
	v_rcp_f32_e32 v85, v85
	v_rcp_f32_e32 v86, v86
	v_rcp_f32_e32 v87, v87
	v_rcp_f32_e32 v88, v88
	v_rcp_f32_e32 v89, v89
	v_pk_mul_f32 v[76:77], v[76:77], v[80:81]
	v_pk_mul_f32 v[78:79], v[78:79], v[84:85]
	v_pk_mul_f32 v[72:73], v[72:73], v[86:87]
	v_pk_mul_f32 v[74:75], v[74:75], v[88:89]
	v_pk_mul_f32 v[68:69], v[68:69], v[76:77]
	v_pk_mul_f32 v[70:71], v[70:71], v[78:79]
	v_pk_mul_f32 v[72:73], v[64:65], v[72:73]
	v_pk_mul_f32 v[74:75], v[66:67], v[74:75]
	v_cvt_pk_bf16_f32 v64, v68, v69
	v_cvt_pk_bf16_f32 v65, v70, v71
	v_cvt_pk_bf16_f32 v66, v72, v73
	v_cvt_pk_bf16_f32 v67, v74, v75
	global_store_dwordx4 v[82:83], v[64:67], off
	s_nop 1
	s_nop 0
	v_add_u32_e32 v65, 0x80, v144
	v_mad_i64_i32 v[66:67], s[22:23], v65, s47, v[146:147]
	v_lshl_add_u64 v[66:67], v[66:67], 0, v[148:149]
	v_fmamk_f32 v64, v233, 0x3a800000, v158
	v_rsq_f32_e32 v64, v64
	s_nop 0
	v_pk_mul_f32 v[62:63], v[62:63], v[64:65] op_sel_hi:[1,0]
	v_pk_mul_f32 v[60:61], v[60:61], v[64:65] op_sel_hi:[1,0]
	v_pk_mul_f32 v[58:59], v[58:59], v[64:65] op_sel_hi:[1,0]
	v_pk_mul_f32 v[56:57], v[56:57], v[64:65] op_sel_hi:[1,0]
	v_pk_mul_f32 v[54:55], v[54:55], v[64:65] op_sel_hi:[1,0]
	v_pk_mul_f32 v[52:53], v[52:53], v[64:65] op_sel_hi:[1,0]
	v_pk_mul_f32 v[50:51], v[50:51], v[64:65] op_sel_hi:[1,0]
	v_pk_mul_f32 v[48:49], v[48:49], v[64:65] op_sel_hi:[1,0]
	v_mul_f32_e32 v64, 0xbfb8aa3b, v60
	v_mul_f32_e32 v65, 0xbfb8aa3b, v61
	v_mul_f32_e32 v68, 0xbfb8aa3b, v62
	v_mul_f32_e32 v69, 0xbfb8aa3b, v63
	v_mul_f32_e32 v70, 0xbfb8aa3b, v56
	v_mul_f32_e32 v71, 0xbfb8aa3b, v57
	v_mul_f32_e32 v72, 0xbfb8aa3b, v58
	v_mul_f32_e32 v73, 0xbfb8aa3b, v59
	v_exp_f32_e32 v64, v64
	v_exp_f32_e32 v65, v65
	v_exp_f32_e32 v68, v68
	v_exp_f32_e32 v69, v69
	v_exp_f32_e32 v70, v70
	v_exp_f32_e32 v71, v71
	v_exp_f32_e32 v72, v72
	v_exp_f32_e32 v73, v73
	v_add_f32_e32 v64, 1.0, v64
	v_add_f32_e32 v65, 1.0, v65
	v_add_f32_e32 v68, 1.0, v68
	v_add_f32_e32 v69, 1.0, v69
	v_add_f32_e32 v70, 1.0, v70
	v_add_f32_e32 v71, 1.0, v71
	v_add_f32_e32 v72, 1.0, v72
	v_add_f32_e32 v73, 1.0, v73
	v_rcp_f32_e32 v64, v64
; __device__ __forceinline__ unsigned cvt_pk_bf16(float lo, float hi) { f32x2_t v = {lo, hi}; bf16x2_t b = __builtin_convertvector(v, bf16x2_t); return __builtin_bit_cast(unsigned, b); }
; __device__ __forceinline__ float silu_f(float g) { return g * __builtin_amdgcn_rcpf(1.0f + __builtin_amdgcn_exp2f(-1.44269504f * g)); }
;     __device__ __forceinline__ void operator()(const f32x4 (&acc)[2][2][4][2], const Unit& u, int wr, int wc, int fr, int fq) const {
;         const int row0 = u.pm * BM + wr * 64 + fr, col0 = u.pn * HALF + wc * 32 + 8 * fq;
; #pragma unroll
;         for (int ai = 0; ai < 2; ++ai)
; #pragma unroll
;             for (int m = 0; m < 4; ++m) {
;                 const int row = row0 + ai * HALF + m * 16;
;                 const float rs = rowss ? __builtin_amdgcn_rsqf(rowss[row] * (1.0f / 1024.0f) + 1e-6f) : 1.0f;
;                 bf16_t* rowp = O + (size_t)row * ldc + col0;
;                 const f32x4 g0 = acc[ai][0][m][0] * rs, g1 = acc[ai][0][m][1] * rs, u0 = acc[ai][1][m][0] * rs, u1 = acc[ai][1][m][1] * rs;
;                 u32x4 w;
;                 w.x = cvt_pk_bf16(silu_f(g0[0]) * u0[0], silu_f(g0[1]) * u0[1]); w.y = cvt_pk_bf16(silu_f(g0[2]) * u0[2], silu_f(g0[3]) * u0[3]);
;                 w.z = cvt_pk_bf16(silu_f(g1[0]) * u1[0], silu_f(g1[1]) * u1[1]); w.w = cvt_pk_bf16(silu_f(g1[2]) * u1[2], silu_f(g1[3]) * u1[3]);
;                 *(u32x4*)rowp = w;
	v_rcp_f32_e32 v65, v65
	v_rcp_f32_e32 v68, v68
	v_rcp_f32_e32 v69, v69
	v_rcp_f32_e32 v70, v70
	v_rcp_f32_e32 v71, v71
	v_rcp_f32_e32 v72, v72
	v_rcp_f32_e32 v73, v73
	v_pk_mul_f32 v[60:61], v[60:61], v[64:65]
	v_pk_mul_f32 v[62:63], v[62:63], v[68:69]
	v_pk_mul_f32 v[56:57], v[56:57], v[70:71]
	v_pk_mul_f32 v[58:59], v[58:59], v[72:73]
	v_pk_mul_f32 v[52:53], v[52:53], v[60:61]
	v_pk_mul_f32 v[54:55], v[54:55], v[62:63]
	v_pk_mul_f32 v[56:57], v[48:49], v[56:57]
	v_pk_mul_f32 v[58:59], v[50:51], v[58:59]
	v_cvt_pk_bf16_f32 v48, v52, v53
	v_cvt_pk_bf16_f32 v49, v54, v55
	v_cvt_pk_bf16_f32 v50, v56, v57
	v_cvt_pk_bf16_f32 v51, v58, v59
	global_store_dwordx4 v[66:67], v[48:51], off
	s_nop 1
	s_nop 0
	v_add_u32_e32 v49, 0x90, v144
	v_mad_i64_i32 v[50:51], s[22:23], v49, s47, v[146:147]
	v_lshl_add_u64 v[50:51], v[50:51], 0, v[148:149]
	v_fmamk_f32 v48, v234, 0x3a800000, v158
	v_rsq_f32_e32 v48, v48
	s_nop 0
	v_pk_mul_f32 v[46:47], v[46:47], v[48:49] op_sel_hi:[1,0]
	v_pk_mul_f32 v[44:45], v[44:45], v[48:49] op_sel_hi:[1,0]
	v_pk_mul_f32 v[42:43], v[42:43], v[48:49] op_sel_hi:[1,0]
	v_pk_mul_f32 v[40:41], v[40:41], v[48:49] op_sel_hi:[1,0]
	v_pk_mul_f32 v[38:39], v[38:39], v[48:49] op_sel_hi:[1,0]
	v_pk_mul_f32 v[36:37], v[36:37], v[48:49] op_sel_hi:[1,0]
	v_pk_mul_f32 v[34:35], v[34:35], v[48:49] op_sel_hi:[1,0]
	v_pk_mul_f32 v[32:33], v[32:33], v[48:49] op_sel_hi:[1,0]
	v_mul_f32_e32 v48, 0xbfb8aa3b, v44
	v_mul_f32_e32 v49, 0xbfb8aa3b, v45
	v_mul_f32_e32 v52, 0xbfb8aa3b, v46
	v_mul_f32_e32 v53, 0xbfb8aa3b, v47
	v_mul_f32_e32 v54, 0xbfb8aa3b, v40
	v_mul_f32_e32 v55, 0xbfb8aa3b, v41
	v_mul_f32_e32 v56, 0xbfb8aa3b, v42
	v_mul_f32_e32 v57, 0xbfb8aa3b, v43
	v_exp_f32_e32 v48, v48
	v_exp_f32_e32 v49, v49
	v_exp_f32_e32 v52, v52
	v_exp_f32_e32 v53, v53
	v_exp_f32_e32 v54, v54
	v_exp_f32_e32 v55, v55
	v_exp_f32_e32 v56, v56
	v_exp_f32_e32 v57, v57
	v_add_f32_e32 v48, 1.0, v48
	v_add_f32_e32 v49, 1.0, v49
	v_add_f32_e32 v52, 1.0, v52
	v_add_f32_e32 v53, 1.0, v53
	v_add_f32_e32 v54, 1.0, v54
	v_add_f32_e32 v55, 1.0, v55
	v_add_f32_e32 v56, 1.0, v56
	v_add_f32_e32 v57, 1.0, v57
	v_rcp_f32_e32 v48, v48
	v_rcp_f32_e32 v49, v49
	v_rcp_f32_e32 v52, v52
	v_rcp_f32_e32 v53, v53
	v_rcp_f32_e32 v54, v54
	v_rcp_f32_e32 v55, v55
	v_rcp_f32_e32 v56, v56
	v_rcp_f32_e32 v57, v57
	v_pk_mul_f32 v[44:45], v[44:45], v[48:49]
	v_pk_mul_f32 v[46:47], v[46:47], v[52:53]
	v_pk_mul_f32 v[40:41], v[40:41], v[54:55]
	v_pk_mul_f32 v[42:43], v[42:43], v[56:57]
	v_pk_mul_f32 v[36:37], v[36:37], v[44:45]
	v_pk_mul_f32 v[38:39], v[38:39], v[46:47]
	v_pk_mul_f32 v[40:41], v[32:33], v[40:41]
	v_pk_mul_f32 v[42:43], v[34:35], v[42:43]
	v_cvt_pk_bf16_f32 v32, v36, v37
	v_cvt_pk_bf16_f32 v33, v38, v39
	v_cvt_pk_bf16_f32 v34, v40, v41
	v_cvt_pk_bf16_f32 v35, v42, v43
	global_store_dwordx4 v[50:51], v[32:35], off
	s_nop 1
	s_nop 0
	v_add_u32_e32 v33, 0xa0, v144
	v_mad_i64_i32 v[34:35], s[22:23], v33, s47, v[146:147]
	v_lshl_add_u64 v[34:35], v[34:35], 0, v[148:149]
	v_fmamk_f32 v32, v235, 0x3a800000, v158
	v_rsq_f32_e32 v32, v32
	s_nop 0
	v_pk_mul_f32 v[30:31], v[30:31], v[32:33] op_sel_hi:[1,0]
	v_pk_mul_f32 v[28:29], v[28:29], v[32:33] op_sel_hi:[1,0]
	v_pk_mul_f32 v[26:27], v[26:27], v[32:33] op_sel_hi:[1,0]
	v_pk_mul_f32 v[24:25], v[24:25], v[32:33] op_sel_hi:[1,0]
	v_pk_mul_f32 v[22:23], v[22:23], v[32:33] op_sel_hi:[1,0]
	v_pk_mul_f32 v[20:21], v[20:21], v[32:33] op_sel_hi:[1,0]
	v_pk_mul_f32 v[18:19], v[18:19], v[32:33] op_sel_hi:[1,0]
	v_pk_mul_f32 v[16:17], v[16:17], v[32:33] op_sel_hi:[1,0]
	v_mul_f32_e32 v32, 0xbfb8aa3b, v28
	v_mul_f32_e32 v33, 0xbfb8aa3b, v29
	v_mul_f32_e32 v36, 0xbfb8aa3b, v30
	v_mul_f32_e32 v37, 0xbfb8aa3b, v31
	v_mul_f32_e32 v38, 0xbfb8aa3b, v24
	v_mul_f32_e32 v39, 0xbfb8aa3b, v25
	v_mul_f32_e32 v40, 0xbfb8aa3b, v26
	v_mul_f32_e32 v41, 0xbfb8aa3b, v27
	v_exp_f32_e32 v32, v32
	v_exp_f32_e32 v33, v33
	v_exp_f32_e32 v36, v36
	v_exp_f32_e32 v37, v37
	v_exp_f32_e32 v38, v38
	v_exp_f32_e32 v39, v39
	v_exp_f32_e32 v40, v40
	v_exp_f32_e32 v41, v41
	v_add_f32_e32 v32, 1.0, v32
	v_add_f32_e32 v33, 1.0, v33
	v_add_f32_e32 v36, 1.0, v36
	v_add_f32_e32 v37, 1.0, v37
	v_add_f32_e32 v38, 1.0, v38
	v_add_f32_e32 v39, 1.0, v39
	v_add_f32_e32 v40, 1.0, v40
	v_add_f32_e32 v41, 1.0, v41
	v_rcp_f32_e32 v32, v32
	v_rcp_f32_e32 v33, v33
	v_rcp_f32_e32 v36, v36
	v_rcp_f32_e32 v37, v37
	v_rcp_f32_e32 v38, v38
	v_rcp_f32_e32 v39, v39
	v_rcp_f32_e32 v40, v40
	v_rcp_f32_e32 v41, v41
	v_pk_mul_f32 v[28:29], v[28:29], v[32:33]
	v_pk_mul_f32 v[30:31], v[30:31], v[36:37]
	v_pk_mul_f32 v[24:25], v[24:25], v[38:39]
	v_pk_mul_f32 v[26:27], v[26:27], v[40:41]
	v_pk_mul_f32 v[20:21], v[20:21], v[28:29]
	v_pk_mul_f32 v[22:23], v[22:23], v[30:31]
	v_pk_mul_f32 v[24:25], v[16:17], v[24:25]
	v_pk_mul_f32 v[26:27], v[18:19], v[26:27]
	v_cvt_pk_bf16_f32 v16, v20, v21
	v_cvt_pk_bf16_f32 v17, v22, v23
	v_cvt_pk_bf16_f32 v18, v24, v25
	v_cvt_pk_bf16_f32 v19, v26, v27
	global_store_dwordx4 v[34:35], v[16:19], off
	s_nop 1
	s_nop 0
	v_add_u32_e32 v17, 0xb0, v144
	v_mad_i64_i32 v[18:19], s[22:23], v17, s47, v[146:147]
	v_lshl_add_u64 v[18:19], v[18:19], 0, v[148:149]
	v_fmamk_f32 v16, v236, 0x3a800000, v158
	v_rsq_f32_e32 v16, v16
	s_nop 0
	v_pk_mul_f32 v[14:15], v[14:15], v[16:17] op_sel_hi:[1,0]
	v_pk_mul_f32 v[12:13], v[12:13], v[16:17] op_sel_hi:[1,0]
	v_pk_mul_f32 v[10:11], v[10:11], v[16:17] op_sel_hi:[1,0]
	v_pk_mul_f32 v[8:9], v[8:9], v[16:17] op_sel_hi:[1,0]
	v_pk_mul_f32 v[6:7], v[6:7], v[16:17] op_sel_hi:[1,0]
	v_pk_mul_f32 v[4:5], v[4:5], v[16:17] op_sel_hi:[1,0]
	v_pk_mul_f32 v[2:3], v[2:3], v[16:17] op_sel_hi:[1,0]
	v_pk_mul_f32 v[0:1], v[0:1], v[16:17] op_sel_hi:[1,0]
	v_mul_f32_e32 v16, 0xbfb8aa3b, v12
	v_mul_f32_e32 v17, 0xbfb8aa3b, v13
	v_mul_f32_e32 v20, 0xbfb8aa3b, v14
	v_mul_f32_e32 v21, 0xbfb8aa3b, v15
	v_mul_f32_e32 v22, 0xbfb8aa3b, v8
	v_mul_f32_e32 v23, 0xbfb8aa3b, v9
	v_mul_f32_e32 v24, 0xbfb8aa3b, v10
	v_mul_f32_e32 v25, 0xbfb8aa3b, v11
	v_exp_f32_e32 v16, v16
	v_exp_f32_e32 v17, v17
	v_exp_f32_e32 v20, v20
	v_exp_f32_e32 v21, v21
	v_exp_f32_e32 v22, v22
	v_exp_f32_e32 v23, v23
	v_exp_f32_e32 v24, v24
	v_exp_f32_e32 v25, v25
	v_add_f32_e32 v16, 1.0, v16
	v_add_f32_e32 v17, 1.0, v17
	v_add_f32_e32 v20, 1.0, v20
	v_add_f32_e32 v21, 1.0, v21
	v_add_f32_e32 v22, 1.0, v22
	v_add_f32_e32 v23, 1.0, v23
	v_add_f32_e32 v24, 1.0, v24
	v_add_f32_e32 v25, 1.0, v25
	v_rcp_f32_e32 v16, v16
	v_rcp_f32_e32 v17, v17
	v_rcp_f32_e32 v20, v20
	v_rcp_f32_e32 v21, v21
	v_rcp_f32_e32 v22, v22
	v_rcp_f32_e32 v23, v23
	v_rcp_f32_e32 v24, v24
	v_rcp_f32_e32 v25, v25
	v_pk_mul_f32 v[12:13], v[12:13], v[16:17]
	v_pk_mul_f32 v[14:15], v[14:15], v[20:21]
	v_pk_mul_f32 v[8:9], v[8:9], v[22:23]
	v_pk_mul_f32 v[10:11], v[10:11], v[24:25]
	v_pk_mul_f32 v[4:5], v[4:5], v[12:13]
	v_pk_mul_f32 v[6:7], v[6:7], v[14:15]
	v_pk_mul_f32 v[8:9], v[0:1], v[8:9]
	v_pk_mul_f32 v[10:11], v[2:3], v[10:11]
	v_cvt_pk_bf16_f32 v0, v4, v5
	v_cvt_pk_bf16_f32 v1, v6, v7
	v_cvt_pk_bf16_f32 v2, v8, v9
	v_cvt_pk_bf16_f32 v3, v10, v11
	global_store_dwordx4 v[18:19], v[0:3], off
	s_cbranch_vccnz .LBB0_1099
; #define PG8_BAR __builtin_amdgcn_s_barrier()
; template <class Epi, class Sched, bool ALIGN_EPI = false, bool SP2 = false>
; __device__ __forceinline__ void gemm_phase(PG8_LAS unsigned char* lds, const Gemm g, const Sched& S, const Epi& E) {
;     ...
;         if (!has_next) break;
; #pragma unroll
;         for (int a = 0; a < 2; ++a)
; #pragma unroll
;             for (int b = 0; b < 2; ++b)
; #pragma unroll
;                 for (int m = 0; m < 4; ++m)
; #pragma unroll
;                     for (int n = 0; n < 2; ++n) acc[a][b][m][n] = (f32x4){0.f, 0.f, 0.f, 0.f};
;         cur = nxt; cA = nA; cB = nB; ++ui;
;         if constexpr (ALIGN_EPI) { if (wr == 1) PG8_BAR; }
	s_andn2_b64 vcc, exec, s[4:5]
	s_cbranch_vccnz .LBB0_1098
	s_barrier
	s_branch .LBB0_1098
